# attention epilogue: 16 gain loads batched before the stores
# speedup vs baseline: 1.0098x; 1.0098x over previous
.LBB0_1029:
	v_mul_f32_e32 v74, v49, v49
	v_fmac_f32_e32 v74, v48, v48
	v_fmac_f32_e32 v74, v50, v50
	v_fmac_f32_e32 v74, v51, v51
	v_fmac_f32_e32 v74, v52, v52
	v_fmac_f32_e32 v74, v53, v53
	v_fmac_f32_e32 v74, v54, v54
	v_fmac_f32_e32 v74, v55, v55
	v_fmac_f32_e32 v74, v56, v56
	v_fmac_f32_e32 v74, v57, v57
	v_fmac_f32_e32 v74, v58, v58
	v_fmac_f32_e32 v74, v59, v59
	v_fmac_f32_e32 v74, v60, v60
	v_fmac_f32_e32 v74, v61, v61
	v_fmac_f32_e32 v74, v62, v62
	v_fmac_f32_e32 v74, v63, v63
	v_fmac_f32_e32 v74, v32, v32
	v_fmac_f32_e32 v74, v33, v33
	v_fmac_f32_e32 v74, v34, v34
	v_fmac_f32_e32 v74, v35, v35
	v_fmac_f32_e32 v74, v36, v36
	v_fmac_f32_e32 v74, v37, v37
	v_fmac_f32_e32 v74, v38, v38
	v_fmac_f32_e32 v74, v39, v39
	v_fmac_f32_e32 v74, v40, v40
	v_fmac_f32_e32 v74, v41, v41
	v_fmac_f32_e32 v74, v42, v42
	v_fmac_f32_e32 v74, v43, v43
	v_fmac_f32_e32 v74, v44, v44
	v_fmac_f32_e32 v74, v45, v45
	v_fmac_f32_e32 v74, v46, v46
	v_fmac_f32_e32 v74, v47, v47
	v_fmac_f32_e32 v74, v16, v16
	v_fmac_f32_e32 v74, v17, v17
	v_fmac_f32_e32 v74, v18, v18
	v_fmac_f32_e32 v74, v19, v19
	v_fmac_f32_e32 v74, v20, v20
	v_fmac_f32_e32 v74, v21, v21
	v_fmac_f32_e32 v74, v22, v22
	v_fmac_f32_e32 v74, v23, v23
	v_fmac_f32_e32 v74, v24, v24
	v_fmac_f32_e32 v74, v25, v25
	v_fmac_f32_e32 v74, v26, v26
	v_fmac_f32_e32 v74, v27, v27
	v_fmac_f32_e32 v74, v28, v28
	v_fmac_f32_e32 v74, v29, v29
	v_fmac_f32_e32 v74, v30, v30
	v_fmac_f32_e32 v74, v31, v31
	v_fmac_f32_e32 v74, v0, v0
	v_fmac_f32_e32 v74, v1, v1
	v_fmac_f32_e32 v74, v2, v2
	v_fmac_f32_e32 v74, v3, v3
	v_fmac_f32_e32 v74, v4, v4
	v_fmac_f32_e32 v74, v5, v5
	v_pk_mul_f32 v[72:73], v[6:7], v[6:7]
	v_pk_mul_f32 v[70:71], v[8:9], v[8:9]
	v_add_f32_e32 v72, v72, v74
	v_add_f32_e32 v72, v73, v72
	v_add_f32_e32 v70, v70, v72
	v_pk_mul_f32 v[68:69], v[10:11], v[10:11]
	v_add_f32_e32 v70, v71, v70
	v_add_f32_e32 v68, v68, v70
	v_pk_mul_f32 v[66:67], v[12:13], v[12:13]
	v_add_f32_e32 v68, v69, v68
	v_add_f32_e32 v66, v66, v68
	v_pk_mul_f32 v[64:65], v[14:15], v[14:15]
	v_add_f32_e32 v66, v67, v66
	v_add_f32_e32 v64, v64, v66
	v_add_f32_e32 v64, v65, v64
	v_mov_b32_e32 v65, v221
	global_load_dwordx4 v[80:83], v[154:155], off
	global_load_dwordx4 v[84:87], v[154:155], off offset:32
	global_load_dwordx4 v[88:91], v[154:155], off offset:64
	global_load_dwordx4 v[92:95], v[154:155], off offset:96
	global_load_dwordx4 v[96:99], v[154:155], off offset:128
	global_load_dwordx4 v[100:103], v[154:155], off offset:160
	global_load_dwordx4 v[104:107], v[154:155], off offset:192
	global_load_dwordx4 v[108:111], v[154:155], off offset:224
	global_load_dwordx4 v[112:115], v[154:155], off offset:256
	global_load_dwordx4 v[116:119], v[154:155], off offset:288
	global_load_dwordx4 v[120:123], v[154:155], off offset:320
	global_load_dwordx4 v[124:127], v[154:155], off offset:352
	global_load_dwordx4 v[130:133], v[154:155], off offset:384
	global_load_dwordx4 v[134:137], v[154:155], off offset:416
	global_load_dwordx4 v[138:141], v[154:155], off offset:448
	global_load_dwordx4 v[142:145], v[154:155], off offset:480
	v_lshlrev_b32_e32 v65, 2, v65
	v_xor_b32_e32 v65, 0x80, v65
	ds_bpermute_b32 v65, v65, v64
	s_mov_b32 s2, 0x800000
	v_lshl_add_u64 v[66:67], v[172:173], 1, s[0:1]
	s_lshl_b32 s18, s14, 1
	v_lshl_add_u64 v[66:67], v[66:67], 0, s[18:19]
	s_waitcnt lgkmcnt(0)
	v_add_f32_e32 v64, v64, v65
	v_fmamk_f32 v64, v64, 0x3c000000, v162
	v_cmp_gt_f32_e32 vcc, s2, v64
	v_mul_f32_e32 v65, 0x4b800000, v64
	v_mov_b32_e32 v169, v129
	v_cndmask_b32_e32 v64, v64, v65, vcc
	v_rsq_f32_e32 v64, v64
	v_lshl_add_u64 v[66:67], v[66:67], 0, v[168:169]
	s_mov_b32 s3, s19
	v_writelane_b32 v252, s2, 12
	v_mul_f32_e32 v65, 0x45800000, v64
	v_cndmask_b32_e32 v64, v64, v65, vcc
	v_mul_f32_e32 v64, v190, v64
	v_writelane_b32 v252, s3, 13
	v_readlane_b32 s2, v252, 2
	s_add_i32 s16, s16, s2
	s_cmpk_gt_i32 s16, 0x3ff
	v_pk_mul_f32 v[0:1], v[0:1], v[64:65] op_sel_hi:[1,0]
	v_pk_mul_f32 v[2:3], v[2:3], v[64:65] op_sel_hi:[1,0]
	v_pk_mul_f32 v[4:5], v[4:5], v[64:65] op_sel_hi:[1,0]
	v_pk_mul_f32 v[6:7], v[6:7], v[64:65] op_sel_hi:[1,0]
	v_pk_mul_f32 v[8:9], v[8:9], v[64:65] op_sel_hi:[1,0]
	v_pk_mul_f32 v[10:11], v[10:11], v[64:65] op_sel_hi:[1,0]
	v_pk_mul_f32 v[12:13], v[12:13], v[64:65] op_sel_hi:[1,0]
	v_pk_mul_f32 v[14:15], v[14:15], v[64:65] op_sel_hi:[1,0]
	v_pk_mul_f32 v[16:17], v[16:17], v[64:65] op_sel_hi:[1,0]
	v_pk_mul_f32 v[18:19], v[18:19], v[64:65] op_sel_hi:[1,0]
	v_pk_mul_f32 v[20:21], v[20:21], v[64:65] op_sel_hi:[1,0]
	v_pk_mul_f32 v[22:23], v[22:23], v[64:65] op_sel_hi:[1,0]
	v_pk_mul_f32 v[24:25], v[24:25], v[64:65] op_sel_hi:[1,0]
	v_pk_mul_f32 v[26:27], v[26:27], v[64:65] op_sel_hi:[1,0]
	v_pk_mul_f32 v[28:29], v[28:29], v[64:65] op_sel_hi:[1,0]
	v_pk_mul_f32 v[30:31], v[30:31], v[64:65] op_sel_hi:[1,0]
	v_pk_mul_f32 v[32:33], v[32:33], v[64:65] op_sel_hi:[1,0]
	v_pk_mul_f32 v[34:35], v[34:35], v[64:65] op_sel_hi:[1,0]
	v_pk_mul_f32 v[36:37], v[36:37], v[64:65] op_sel_hi:[1,0]
	v_pk_mul_f32 v[38:39], v[38:39], v[64:65] op_sel_hi:[1,0]
	v_pk_mul_f32 v[40:41], v[40:41], v[64:65] op_sel_hi:[1,0]
	v_pk_mul_f32 v[42:43], v[42:43], v[64:65] op_sel_hi:[1,0]
	v_pk_mul_f32 v[44:45], v[44:45], v[64:65] op_sel_hi:[1,0]
	v_pk_mul_f32 v[46:47], v[46:47], v[64:65] op_sel_hi:[1,0]
	v_pk_mul_f32 v[48:49], v[48:49], v[64:65] op_sel_hi:[1,0]
	v_pk_mul_f32 v[50:51], v[50:51], v[64:65] op_sel_hi:[1,0]
	v_pk_mul_f32 v[52:53], v[52:53], v[64:65] op_sel_hi:[1,0]
	v_pk_mul_f32 v[54:55], v[54:55], v[64:65] op_sel_hi:[1,0]
	v_pk_mul_f32 v[56:57], v[56:57], v[64:65] op_sel_hi:[1,0]
	v_pk_mul_f32 v[58:59], v[58:59], v[64:65] op_sel_hi:[1,0]
	v_pk_mul_f32 v[60:61], v[60:61], v[64:65] op_sel_hi:[1,0]
	v_pk_mul_f32 v[62:63], v[62:63], v[64:65] op_sel_hi:[1,0]
	s_waitcnt vmcnt(0)
	v_pk_mul_f32 v[48:49], v[80:81], v[48:49]
	v_pk_mul_f32 v[50:51], v[82:83], v[50:51]
	v_cvt_pk_bf16_f32 v48, v48, v49
	v_cvt_pk_bf16_f32 v49, v50, v51
	global_store_dwordx2 v[66:67], v[48:49], off
	v_pk_mul_f32 v[52:53], v[84:85], v[52:53]
	v_pk_mul_f32 v[54:55], v[86:87], v[54:55]
	v_cvt_pk_bf16_f32 v52, v52, v53
	v_cvt_pk_bf16_f32 v53, v54, v55
	global_store_dwordx2 v[66:67], v[52:53], off offset:16
	v_pk_mul_f32 v[56:57], v[88:89], v[56:57]
	v_pk_mul_f32 v[58:59], v[90:91], v[58:59]
	v_cvt_pk_bf16_f32 v56, v56, v57
	v_cvt_pk_bf16_f32 v57, v58, v59
	global_store_dwordx2 v[66:67], v[56:57], off offset:32
	v_pk_mul_f32 v[60:61], v[92:93], v[60:61]
	v_pk_mul_f32 v[62:63], v[94:95], v[62:63]
	v_cvt_pk_bf16_f32 v60, v60, v61
	v_cvt_pk_bf16_f32 v61, v62, v63
	global_store_dwordx2 v[66:67], v[60:61], off offset:48
	v_pk_mul_f32 v[32:33], v[96:97], v[32:33]
	v_pk_mul_f32 v[34:35], v[98:99], v[34:35]
	v_cvt_pk_bf16_f32 v32, v32, v33
	v_cvt_pk_bf16_f32 v33, v34, v35
	global_store_dwordx2 v[66:67], v[32:33], off offset:64
	v_pk_mul_f32 v[36:37], v[100:101], v[36:37]
	v_pk_mul_f32 v[38:39], v[102:103], v[38:39]
	v_cvt_pk_bf16_f32 v36, v36, v37
	v_cvt_pk_bf16_f32 v37, v38, v39
	global_store_dwordx2 v[66:67], v[36:37], off offset:80
	v_pk_mul_f32 v[40:41], v[104:105], v[40:41]
	v_pk_mul_f32 v[42:43], v[106:107], v[42:43]
	v_cvt_pk_bf16_f32 v40, v40, v41
	v_cvt_pk_bf16_f32 v41, v42, v43
	global_store_dwordx2 v[66:67], v[40:41], off offset:96
	v_pk_mul_f32 v[44:45], v[108:109], v[44:45]
	v_pk_mul_f32 v[46:47], v[110:111], v[46:47]
	v_cvt_pk_bf16_f32 v44, v44, v45
	v_cvt_pk_bf16_f32 v45, v46, v47
	global_store_dwordx2 v[66:67], v[44:45], off offset:112
	v_pk_mul_f32 v[16:17], v[112:113], v[16:17]
	v_pk_mul_f32 v[18:19], v[114:115], v[18:19]
	v_cvt_pk_bf16_f32 v16, v16, v17
	v_cvt_pk_bf16_f32 v17, v18, v19
	global_store_dwordx2 v[66:67], v[16:17], off offset:128
	v_pk_mul_f32 v[20:21], v[116:117], v[20:21]
	v_pk_mul_f32 v[22:23], v[118:119], v[22:23]
	v_cvt_pk_bf16_f32 v20, v20, v21
	v_cvt_pk_bf16_f32 v21, v22, v23
	global_store_dwordx2 v[66:67], v[20:21], off offset:144
	v_pk_mul_f32 v[24:25], v[120:121], v[24:25]
	v_pk_mul_f32 v[26:27], v[122:123], v[26:27]
	v_cvt_pk_bf16_f32 v24, v24, v25
	v_cvt_pk_bf16_f32 v25, v26, v27
	global_store_dwordx2 v[66:67], v[24:25], off offset:160
	v_pk_mul_f32 v[28:29], v[124:125], v[28:29]
	v_pk_mul_f32 v[30:31], v[126:127], v[30:31]
	v_cvt_pk_bf16_f32 v28, v28, v29
	v_cvt_pk_bf16_f32 v29, v30, v31
	global_store_dwordx2 v[66:67], v[28:29], off offset:176
	v_pk_mul_f32 v[0:1], v[130:131], v[0:1]
	v_pk_mul_f32 v[2:3], v[132:133], v[2:3]
	v_cvt_pk_bf16_f32 v0, v0, v1
	v_cvt_pk_bf16_f32 v1, v2, v3
	global_store_dwordx2 v[66:67], v[0:1], off offset:192
	v_pk_mul_f32 v[4:5], v[134:135], v[4:5]
	v_pk_mul_f32 v[6:7], v[136:137], v[6:7]
	v_cvt_pk_bf16_f32 v4, v4, v5
	v_cvt_pk_bf16_f32 v5, v6, v7
	global_store_dwordx2 v[66:67], v[4:5], off offset:208
	v_pk_mul_f32 v[8:9], v[138:139], v[8:9]
	v_pk_mul_f32 v[10:11], v[140:141], v[10:11]
	v_cvt_pk_bf16_f32 v8, v8, v9
	v_cvt_pk_bf16_f32 v9, v10, v11
	global_store_dwordx2 v[66:67], v[8:9], off offset:224
	v_pk_mul_f32 v[12:13], v[142:143], v[12:13]
	v_pk_mul_f32 v[14:15], v[144:145], v[14:15]
	v_cvt_pk_bf16_f32 v12, v12, v13
	v_cvt_pk_bf16_f32 v13, v14, v15
	global_store_dwordx2 v[66:67], v[12:13], off offset:240
	s_cbranch_scc1 .LBB0_1047
